# slot table requantized: gate/up tail slots 2 full rounds, down slots 3 full rounds
# baseline (speedup 1.0000x reference)
; __device__ void phase_convert(PP p, unsigned char* smem) {
;     ...
;   int t = blockIdx.x;
;   if (t < NT_ALL) {
;     cvt_decode(p, t, src, ld, dst, K, k0, n0, n4);
; #pragma unroll
;     for (int i = 0; i < 4; ++i) cur[i] = src ? *(const f32x4*)(src + (size_t)(kl + 16 * i) * ld) : (f32x4){0.f, 0.f, 0.f, 0.f};
;   }
;   for (; t < NT_ALL; t += gridDim.x) {
;     const int tn = t + gridDim.x;
;     const float* src2 = nullptr; int ld2 = 0, K2, k02, n02; bf16_t* dst2;
.Lcvt_t0:
	s_mov_b32 s98, 352
	s_mov_b32 s99, 768
	s_mov_b32 s100, 48
	s_branch .Lcvt_go
.Lcvt_t1:
	s_mov_b32 s98, 768
	s_mov_b32 s99, 1152
	s_mov_b32 s100, 128
	s_branch .Lcvt_go

; __device__ void phase_convert(PP p, unsigned char* smem) {
;     ...
;   int t = blockIdx.x;
;   if (t < NT_ALL) {
;     cvt_decode(p, t, src, ld, dst, K, k0, n0, n4);
; #pragma unroll
;     for (int i = 0; i < 4; ++i) cur[i] = src ? *(const f32x4*)(src + (size_t)(kl + 16 * i) * ld) : (f32x4){0.f, 0.f, 0.f, 0.f};
;   }
;   for (; t < NT_ALL; t += gridDim.x) {
;     const int tn = t + gridDim.x;
;     const float* src2 = nullptr; int ld2 = 0, K2, k02, n02; bf16_t* dst2;
.Lcvt_t9:
	s_mov_b32 s98, 1952
	s_mov_b32 s99, 2368
	s_mov_b32 s100, 48
	s_branch .Lcvt_go
.Lcvt_t10:
	s_mov_b32 s98, 2368
	s_mov_b32 s99, 2752
	s_mov_b32 s100, 128
	s_branch .Lcvt_go
.Lcvt_t12:
	s_mov_b32 s98, 2752
	s_mov_b32 s99, 3168
	s_mov_b32 s100, 48
	s_branch .Lcvt_go
.Lcvt_t13:
	s_mov_b32 s98, 3168
	s_mov_b32 s99, 3552
	s_mov_b32 s100, 128
	s_branch .Lcvt_go
